# conservative waits: residual-epilogue waits count only younger loads; FFN_UP epilogue rewrite with the common full-drain tail; RESID top drain removed
# speedup vs baseline: 1.0094x; 1.0094x over previous
; DI u32x2 pk4(f32x4 v) { u32x2 r; r.x = cvt_pk(v[0], v[1]); r.y = cvt_pk(v[2], v[3]); return r; }
; DI void gemm_phase(LAS unsigned char* lds, const GemmDesc& d, float* __restrict__ X) {
;     ...
; #pragma unroll
;       for (int ai = 0; ai < 2; ++ai)
; #pragma unroll
;         for (int m = 0; m < 4; ++m) {
;           const int row = pm * 256 + 128 * ai + 16 * m + rb; float ss = 0.f;
; #pragma unroll
;           for (int bj = 0; bj < 2; ++bj) {
;             const size_t o = (size_t)row * DM + pn * 256 + 128 * bj + cb;
;             const u32x4 xw = *(const u32x4*)(d.O0 + o); u32x4 ow;
; #pragma unroll
;             for (int n = 0; n < 2; ++n) {
;               const unsigned w0 = n ? xw.z : xw.x, w1 = n ? xw.w : xw.y;
;               f32x4 xo; xo[0] = __uint_as_float(w0 << 16); xo[1] = __uint_as_float(w0 & 0xffff0000u); xo[2] = __uint_as_float(w1 << 16); xo[3] = __uint_as_float(w1 & 0xffff0000u);
;               const f32x4 xn = xo + acc[ai][bj][m][n] * alpha;
;               ss += (xn[0] * xn[0] + xn[1] * xn[1]) + (xn[2] * xn[2] + xn[3] * xn[3]);
;               const u32x2 pw = pk4(xn); if (n) { ow.z = pw.x; ow.w = pw.y; } else { ow.x = pw.x; ow.y = pw.y; }
;             }
;             *(u32x4*)(d.O0 + o) = ow;
;           }
;           ss += __shfl_xor(ss, 16); ss += __shfl_xor(ss, 32);
;           if (fq == 0) red[wc * 256 + 128 * ai + 16 * m + rb] = ss;
;           asm volatile("" ::: "memory");
;         }
.LBB0_525:
	s_or_b64 exec, exec, s[44:45]
	v_or_b32_e32 v114, 16, v132
	s_waitcnt lgkmcnt(0)
	v_ashrrev_i32_e32 v115, 31, v114
	v_lshlrev_b64 v[114:115], 11, v[114:115]
	v_lshl_add_u64 v[114:115], s[28:29], 0, v[114:115]
	v_lshl_add_u64 v[114:115], v[130:131], 1, v[114:115]
	s_waitcnt vmcnt(11)
	v_mov_b32_e32 v118, v170
	v_mov_b32_e32 v119, v171
	v_mov_b32_e32 v120, v172
	v_mov_b32_e32 v121, v173
	v_add_u32_e32 v252, 0x58000, v243
	global_load_dwordx4 v[170:173], v252, s[28:29]
	s_nop 0
	v_lshlrev_b32_e32 v122, 16, v118
	v_and_b32_e32 v123, 0xffff0000, v118
	v_lshlrev_b32_e32 v118, 16, v119
	v_and_b32_e32 v119, 0xffff0000, v119
	v_pk_fma_f32 v[112:113], s[66:67], v[112:113], v[118:119]
	v_pk_fma_f32 v[110:111], s[60:61], v[110:111], v[122:123]
	v_mul_f32_e32 v119, v113, v113
	v_mul_f32_e32 v118, v111, v111
	v_fmac_f32_e32 v118, v110, v110
	v_fmac_f32_e32 v119, v112, v112
	v_add_f32_e32 v122, v118, v119
	v_cvt_pk_bf16_f32 v110, v110, v111
	v_cvt_pk_bf16_f32 v111, v112, v113
	v_lshlrev_b32_e32 v112, 16, v120
	v_and_b32_e32 v113, 0xffff0000, v120
	v_lshlrev_b32_e32 v118, 16, v121
	v_and_b32_e32 v119, 0xffff0000, v121
	v_pk_fma_f32 v[108:109], s[66:67], v[108:109], v[118:119]
	v_pk_fma_f32 v[106:107], s[60:61], v[106:107], v[112:113]
	v_mul_f32_e32 v113, v109, v109
	v_mul_f32_e32 v112, v107, v107
	v_fmac_f32_e32 v112, v106, v106
	v_fmac_f32_e32 v113, v108, v108
	v_add_f32_e32 v112, v112, v113
	v_add_f32_e32 v118, v122, v112
	v_cvt_pk_bf16_f32 v112, v106, v107
	v_cvt_pk_bf16_f32 v113, v108, v109
	s_waitcnt vmcnt(11)
	v_mov_b32_e32 v106, v184
	v_mov_b32_e32 v107, v185
	v_mov_b32_e32 v108, v186
	v_mov_b32_e32 v109, v187
	v_add_u32_e32 v252, 0x58000, v243
	global_load_dwordx4 v[184:187], v252, s[28:29] offset:256
	s_nop 0
	global_store_dwordx4 v[114:115], v[110:113], off
	s_nop 0
	s_nop 0
	v_lshlrev_b32_e32 v110, 16, v106
	v_and_b32_e32 v111, 0xffff0000, v106
	v_lshlrev_b32_e32 v106, 16, v107
	v_and_b32_e32 v107, 0xffff0000, v107
	v_pk_fma_f32 v[104:105], s[66:67], v[104:105], v[106:107]
	v_pk_fma_f32 v[102:103], s[60:61], v[102:103], v[110:111]
	v_mul_f32_e32 v107, v105, v105
	v_mul_f32_e32 v106, v103, v103
	v_fmac_f32_e32 v106, v102, v102
	v_fmac_f32_e32 v107, v104, v104
	v_add_f32_e32 v106, v106, v107
	v_add_f32_e32 v110, v118, v106
	v_cvt_pk_bf16_f32 v102, v102, v103
	v_cvt_pk_bf16_f32 v103, v104, v105
	v_lshlrev_b32_e32 v104, 16, v108
	v_and_b32_e32 v105, 0xffff0000, v108
	v_lshlrev_b32_e32 v106, 16, v109
	v_and_b32_e32 v107, 0xffff0000, v109
	v_pk_fma_f32 v[100:101], s[66:67], v[100:101], v[106:107]
	v_pk_fma_f32 v[98:99], s[60:61], v[98:99], v[104:105]
	v_mul_f32_e32 v105, v101, v101
	v_mul_f32_e32 v104, v99, v99
	v_fmac_f32_e32 v104, v98, v98
	v_fmac_f32_e32 v105, v100, v100
	v_add_f32_e32 v104, v104, v105
	v_add_f32_e32 v106, v104, v110
	v_cvt_pk_bf16_f32 v104, v98, v99
	ds_bpermute_b32 v98, v116, v106
	v_cvt_pk_bf16_f32 v105, v100, v101
	global_store_dwordx4 v[114:115], v[102:105], off offset:256
	s_waitcnt lgkmcnt(0)
	v_add_f32_e32 v98, v106, v98
	ds_bpermute_b32 v99, v117, v98
	s_and_saveexec_b64 s[44:45], vcc
	s_cbranch_execz .LBB0_527
	s_waitcnt lgkmcnt(0)
	v_add_f32_e32 v98, v98, v99
	ds_write_b32 v0, v98 offset:64
.LBB0_527:
	s_or_b64 exec, exec, s[44:45]
	v_or_b32_e32 v98, 32, v132
	s_waitcnt lgkmcnt(0)
	v_ashrrev_i32_e32 v99, 31, v98
	v_lshlrev_b64 v[98:99], 11, v[98:99]
	v_lshl_add_u64 v[98:99], s[28:29], 0, v[98:99]
	v_lshl_add_u64 v[98:99], v[130:131], 1, v[98:99]
	s_waitcnt vmcnt(11)
	v_mov_b32_e32 v100, v188
	v_mov_b32_e32 v101, v189
	v_mov_b32_e32 v102, v190
	v_mov_b32_e32 v103, v191
	s_nop 0
	v_lshlrev_b32_e32 v104, 16, v100
	v_and_b32_e32 v105, 0xffff0000, v100
	v_lshlrev_b32_e32 v100, 16, v101
	v_and_b32_e32 v101, 0xffff0000, v101
	v_pk_fma_f32 v[96:97], s[66:67], v[96:97], v[100:101]
	v_pk_fma_f32 v[94:95], s[60:61], v[94:95], v[104:105]
	v_mul_f32_e32 v101, v97, v97
	v_mul_f32_e32 v100, v95, v95
	v_fmac_f32_e32 v100, v94, v94
	v_fmac_f32_e32 v101, v96, v96
	v_add_f32_e32 v104, v100, v101
	v_cvt_pk_bf16_f32 v94, v94, v95
	v_cvt_pk_bf16_f32 v95, v96, v97
	v_lshlrev_b32_e32 v96, 16, v102
	v_and_b32_e32 v97, 0xffff0000, v102
	v_lshlrev_b32_e32 v100, 16, v103
	v_and_b32_e32 v101, 0xffff0000, v103
	v_pk_fma_f32 v[92:93], s[66:67], v[92:93], v[100:101]
	v_pk_fma_f32 v[90:91], s[60:61], v[90:91], v[96:97]
	v_mul_f32_e32 v97, v93, v93
	v_mul_f32_e32 v96, v91, v91
	v_fmac_f32_e32 v96, v90, v90
	v_fmac_f32_e32 v97, v92, v92
	v_add_f32_e32 v96, v96, v97
	v_add_f32_e32 v100, v104, v96
	v_cvt_pk_bf16_f32 v96, v90, v91
	v_cvt_pk_bf16_f32 v97, v92, v93
	s_waitcnt vmcnt(10)
	v_mov_b32_e32 v90, v216
	v_mov_b32_e32 v91, v217
	v_mov_b32_e32 v92, v218
	v_mov_b32_e32 v93, v219
	s_nop 0
	global_store_dwordx4 v[98:99], v[94:97], off
	s_nop 0
	s_nop 0
	v_lshlrev_b32_e32 v94, 16, v90
	v_and_b32_e32 v95, 0xffff0000, v90
	v_lshlrev_b32_e32 v90, 16, v91
	v_and_b32_e32 v91, 0xffff0000, v91
	v_pk_fma_f32 v[88:89], s[66:67], v[88:89], v[90:91]
	v_pk_fma_f32 v[86:87], s[60:61], v[86:87], v[94:95]
	v_mul_f32_e32 v91, v89, v89
	v_mul_f32_e32 v90, v87, v87
	v_fmac_f32_e32 v90, v86, v86
	v_fmac_f32_e32 v91, v88, v88
	v_add_f32_e32 v90, v90, v91
	v_add_f32_e32 v94, v100, v90
	v_cvt_pk_bf16_f32 v86, v86, v87
	v_cvt_pk_bf16_f32 v87, v88, v89
	v_lshlrev_b32_e32 v88, 16, v92
	v_and_b32_e32 v89, 0xffff0000, v92
	v_lshlrev_b32_e32 v90, 16, v93
	v_and_b32_e32 v91, 0xffff0000, v93
	v_pk_fma_f32 v[84:85], s[66:67], v[84:85], v[90:91]
	v_pk_fma_f32 v[82:83], s[60:61], v[82:83], v[88:89]
	v_mul_f32_e32 v89, v85, v85
	v_mul_f32_e32 v88, v83, v83
	v_fmac_f32_e32 v88, v82, v82
	v_fmac_f32_e32 v89, v84, v84
	v_add_f32_e32 v88, v88, v89
	v_add_f32_e32 v90, v88, v94
	v_cvt_pk_bf16_f32 v88, v82, v83
	ds_bpermute_b32 v82, v116, v90
	v_cvt_pk_bf16_f32 v89, v84, v85
	global_store_dwordx4 v[98:99], v[86:89], off offset:256
	s_waitcnt lgkmcnt(0)
	v_add_f32_e32 v82, v90, v82
	ds_bpermute_b32 v83, v117, v82
	s_and_saveexec_b64 s[44:45], vcc
	s_cbranch_execz .LBB0_529
	s_waitcnt lgkmcnt(0)
	v_add_f32_e32 v82, v82, v83
	ds_write_b32 v0, v82 offset:128
; DI u32x2 pk4(f32x4 v) { u32x2 r; r.x = cvt_pk(v[0], v[1]); r.y = cvt_pk(v[2], v[3]); return r; }
; DI void gemm_phase(LAS unsigned char* lds, const GemmDesc& d, float* __restrict__ X) {
;     ...
; #pragma unroll
;       for (int ai = 0; ai < 2; ++ai)
; #pragma unroll
;         for (int m = 0; m < 4; ++m) {
;           const int row = pm * 256 + 128 * ai + 16 * m + rb; float ss = 0.f;
; #pragma unroll
;           for (int bj = 0; bj < 2; ++bj) {
;             const size_t o = (size_t)row * DM + pn * 256 + 128 * bj + cb;
;             const u32x4 xw = *(const u32x4*)(d.O0 + o); u32x4 ow;
; #pragma unroll
;             for (int n = 0; n < 2; ++n) {
;               const unsigned w0 = n ? xw.z : xw.x, w1 = n ? xw.w : xw.y;
;               f32x4 xo; xo[0] = __uint_as_float(w0 << 16); xo[1] = __uint_as_float(w0 & 0xffff0000u); xo[2] = __uint_as_float(w1 << 16); xo[3] = __uint_as_float(w1 & 0xffff0000u);
;               const f32x4 xn = xo + acc[ai][bj][m][n] * alpha;
;               ss += (xn[0] * xn[0] + xn[1] * xn[1]) + (xn[2] * xn[2] + xn[3] * xn[3]);
;               const u32x2 pw = pk4(xn); if (n) { ow.z = pw.x; ow.w = pw.y; } else { ow.x = pw.x; ow.y = pw.y; }
;             }
;             *(u32x4*)(d.O0 + o) = ow;
;           }
;           ss += __shfl_xor(ss, 16); ss += __shfl_xor(ss, 32);
;           if (fq == 0) red[wc * 256 + 128 * ai + 16 * m + rb] = ss;
;           asm volatile("" ::: "memory");
;         }
.LBB0_529:
	s_or_b64 exec, exec, s[44:45]
	v_or_b32_e32 v82, 48, v132
	s_waitcnt lgkmcnt(0)
	v_ashrrev_i32_e32 v83, 31, v82
	v_lshlrev_b64 v[82:83], 11, v[82:83]
	v_lshl_add_u64 v[82:83], s[28:29], 0, v[82:83]
	v_lshl_add_u64 v[82:83], v[130:131], 1, v[82:83]
	s_waitcnt vmcnt(9)
	v_mov_b32_e32 v84, v222
	v_mov_b32_e32 v85, v223
	v_mov_b32_e32 v86, v224
	v_mov_b32_e32 v87, v225
	s_nop 0
	v_lshlrev_b32_e32 v88, 16, v84
	v_and_b32_e32 v89, 0xffff0000, v84
	v_lshlrev_b32_e32 v84, 16, v85
	v_and_b32_e32 v85, 0xffff0000, v85
	v_pk_fma_f32 v[80:81], s[66:67], v[80:81], v[84:85]
	v_pk_fma_f32 v[78:79], s[60:61], v[78:79], v[88:89]
	v_mul_f32_e32 v85, v81, v81
	v_mul_f32_e32 v84, v79, v79
	v_fmac_f32_e32 v84, v78, v78
	v_fmac_f32_e32 v85, v80, v80
	v_add_f32_e32 v88, v84, v85
	v_cvt_pk_bf16_f32 v78, v78, v79
	v_cvt_pk_bf16_f32 v79, v80, v81
	v_lshlrev_b32_e32 v80, 16, v86
	v_and_b32_e32 v81, 0xffff0000, v86
	v_lshlrev_b32_e32 v84, 16, v87
	v_and_b32_e32 v85, 0xffff0000, v87
	v_pk_fma_f32 v[76:77], s[66:67], v[76:77], v[84:85]
	v_pk_fma_f32 v[74:75], s[60:61], v[74:75], v[80:81]
	v_mul_f32_e32 v81, v77, v77
	v_mul_f32_e32 v80, v75, v75
	v_fmac_f32_e32 v80, v74, v74
	v_fmac_f32_e32 v81, v76, v76
	v_add_f32_e32 v80, v80, v81
	v_add_f32_e32 v84, v88, v80
	v_cvt_pk_bf16_f32 v80, v74, v75
	v_cvt_pk_bf16_f32 v81, v76, v77
	s_waitcnt vmcnt(8)
	v_mov_b32_e32 v74, v226
	v_mov_b32_e32 v75, v227
	v_mov_b32_e32 v76, v228
	v_mov_b32_e32 v77, v229
	s_nop 0
	global_store_dwordx4 v[82:83], v[78:81], off
	s_nop 0
	s_nop 0
	v_lshlrev_b32_e32 v78, 16, v74
	v_and_b32_e32 v79, 0xffff0000, v74
	v_lshlrev_b32_e32 v74, 16, v75
	v_and_b32_e32 v75, 0xffff0000, v75
	v_pk_fma_f32 v[72:73], s[66:67], v[72:73], v[74:75]
	v_pk_fma_f32 v[70:71], s[60:61], v[70:71], v[78:79]
	v_mul_f32_e32 v75, v73, v73
	v_mul_f32_e32 v74, v71, v71
	v_fmac_f32_e32 v74, v70, v70
	v_fmac_f32_e32 v75, v72, v72
	v_add_f32_e32 v74, v74, v75
	v_add_f32_e32 v78, v84, v74
	v_cvt_pk_bf16_f32 v70, v70, v71
	v_cvt_pk_bf16_f32 v71, v72, v73
	v_lshlrev_b32_e32 v72, 16, v76
	v_and_b32_e32 v73, 0xffff0000, v76
	v_lshlrev_b32_e32 v74, 16, v77
	v_and_b32_e32 v75, 0xffff0000, v77
	v_pk_fma_f32 v[68:69], s[66:67], v[68:69], v[74:75]
	v_pk_fma_f32 v[66:67], s[60:61], v[66:67], v[72:73]
	v_mul_f32_e32 v73, v69, v69
	v_mul_f32_e32 v72, v67, v67
	v_fmac_f32_e32 v72, v66, v66
	v_fmac_f32_e32 v73, v68, v68
	v_add_f32_e32 v72, v72, v73
	v_add_f32_e32 v74, v72, v78
	v_cvt_pk_bf16_f32 v72, v66, v67
	ds_bpermute_b32 v66, v116, v74
	v_cvt_pk_bf16_f32 v73, v68, v69
	global_store_dwordx4 v[82:83], v[70:73], off offset:256
	s_waitcnt lgkmcnt(0)
	v_add_f32_e32 v66, v74, v66
	ds_bpermute_b32 v67, v117, v66
	s_and_saveexec_b64 s[44:45], vcc
	s_cbranch_execz .LBB0_531
	s_waitcnt lgkmcnt(0)
	v_add_f32_e32 v66, v66, v67
	ds_write_b32 v0, v66 offset:192
.LBB0_531:
	s_or_b64 exec, exec, s[44:45]
	v_add_u32_e32 v66, 0x80, v132
	s_waitcnt lgkmcnt(0)
	v_ashrrev_i32_e32 v67, 31, v66
	v_lshlrev_b64 v[66:67], 11, v[66:67]
	v_lshl_add_u64 v[66:67], s[28:29], 0, v[66:67]
	v_lshl_add_u64 v[66:67], v[130:131], 1, v[66:67]
	s_waitcnt vmcnt(7)
	v_mov_b32_e32 v68, v230
	v_mov_b32_e32 v69, v231
	v_mov_b32_e32 v70, v232
	v_mov_b32_e32 v71, v233
	s_nop 0
	v_lshlrev_b32_e32 v72, 16, v68
	v_and_b32_e32 v73, 0xffff0000, v68
	v_lshlrev_b32_e32 v68, 16, v69
	v_and_b32_e32 v69, 0xffff0000, v69
	v_pk_fma_f32 v[64:65], s[66:67], v[64:65], v[68:69]
	v_pk_fma_f32 v[62:63], s[60:61], v[62:63], v[72:73]
	v_mul_f32_e32 v69, v65, v65
	v_mul_f32_e32 v68, v63, v63
	v_fmac_f32_e32 v68, v62, v62
	v_fmac_f32_e32 v69, v64, v64
	v_add_f32_e32 v72, v68, v69
	v_cvt_pk_bf16_f32 v62, v62, v63
	v_cvt_pk_bf16_f32 v63, v64, v65
	v_lshlrev_b32_e32 v64, 16, v70
	v_and_b32_e32 v65, 0xffff0000, v70
	v_lshlrev_b32_e32 v68, 16, v71
	v_and_b32_e32 v69, 0xffff0000, v71
	v_pk_fma_f32 v[60:61], s[66:67], v[60:61], v[68:69]
	v_pk_fma_f32 v[58:59], s[60:61], v[58:59], v[64:65]
	v_mul_f32_e32 v65, v61, v61
	v_mul_f32_e32 v64, v59, v59
	v_fmac_f32_e32 v64, v58, v58
	v_fmac_f32_e32 v65, v60, v60
	v_add_f32_e32 v64, v64, v65
	v_add_f32_e32 v68, v72, v64
	v_cvt_pk_bf16_f32 v64, v58, v59
	v_cvt_pk_bf16_f32 v65, v60, v61
	s_waitcnt vmcnt(6)
	v_mov_b32_e32 v58, v234
	v_mov_b32_e32 v59, v235
	v_mov_b32_e32 v60, v236
	v_mov_b32_e32 v61, v237
	s_nop 0
	global_store_dwordx4 v[66:67], v[62:65], off
	s_nop 0
	s_nop 0
	v_lshlrev_b32_e32 v62, 16, v58
	v_and_b32_e32 v63, 0xffff0000, v58
	v_lshlrev_b32_e32 v58, 16, v59
	v_and_b32_e32 v59, 0xffff0000, v59
	v_pk_fma_f32 v[56:57], s[66:67], v[56:57], v[58:59]
	v_pk_fma_f32 v[54:55], s[60:61], v[54:55], v[62:63]
	v_mul_f32_e32 v59, v57, v57
	v_mul_f32_e32 v58, v55, v55
	v_fmac_f32_e32 v58, v54, v54
	v_fmac_f32_e32 v59, v56, v56
	v_add_f32_e32 v58, v58, v59
	v_add_f32_e32 v62, v68, v58
	v_cvt_pk_bf16_f32 v54, v54, v55
	v_cvt_pk_bf16_f32 v55, v56, v57
	v_lshlrev_b32_e32 v56, 16, v60
	v_and_b32_e32 v57, 0xffff0000, v60
	v_lshlrev_b32_e32 v58, 16, v61
	v_and_b32_e32 v59, 0xffff0000, v61
	v_pk_fma_f32 v[52:53], s[66:67], v[52:53], v[58:59]
	v_pk_fma_f32 v[50:51], s[60:61], v[50:51], v[56:57]
	v_mul_f32_e32 v57, v53, v53
	v_mul_f32_e32 v56, v51, v51
	v_fmac_f32_e32 v56, v50, v50
	v_fmac_f32_e32 v57, v52, v52
	v_add_f32_e32 v56, v56, v57
	v_add_f32_e32 v58, v56, v62
	v_cvt_pk_bf16_f32 v56, v50, v51
	ds_bpermute_b32 v50, v116, v58
	v_cvt_pk_bf16_f32 v57, v52, v53
	global_store_dwordx4 v[66:67], v[54:57], off offset:256
	s_waitcnt lgkmcnt(0)
	v_add_f32_e32 v50, v58, v50
	ds_bpermute_b32 v51, v117, v50
	s_and_saveexec_b64 s[44:45], vcc
	s_cbranch_execz .LBB0_533
	s_waitcnt lgkmcnt(0)
	v_add_f32_e32 v50, v50, v51
	ds_write_b32 v0, v50 offset:512
; DI u32x2 pk4(f32x4 v) { u32x2 r; r.x = cvt_pk(v[0], v[1]); r.y = cvt_pk(v[2], v[3]); return r; }
; DI void gemm_phase(LAS unsigned char* lds, const GemmDesc& d, float* __restrict__ X) {
;     ...
; #pragma unroll
;       for (int ai = 0; ai < 2; ++ai)
; #pragma unroll
;         for (int m = 0; m < 4; ++m) {
;           const int row = pm * 256 + 128 * ai + 16 * m + rb; float ss = 0.f;
; #pragma unroll
;           for (int bj = 0; bj < 2; ++bj) {
;             const size_t o = (size_t)row * DM + pn * 256 + 128 * bj + cb;
;             const u32x4 xw = *(const u32x4*)(d.O0 + o); u32x4 ow;
; #pragma unroll
;             for (int n = 0; n < 2; ++n) {
;               const unsigned w0 = n ? xw.z : xw.x, w1 = n ? xw.w : xw.y;
;               f32x4 xo; xo[0] = __uint_as_float(w0 << 16); xo[1] = __uint_as_float(w0 & 0xffff0000u); xo[2] = __uint_as_float(w1 << 16); xo[3] = __uint_as_float(w1 & 0xffff0000u);
;               const f32x4 xn = xo + acc[ai][bj][m][n] * alpha;
;               ss += (xn[0] * xn[0] + xn[1] * xn[1]) + (xn[2] * xn[2] + xn[3] * xn[3]);
;               const u32x2 pw = pk4(xn); if (n) { ow.z = pw.x; ow.w = pw.y; } else { ow.x = pw.x; ow.y = pw.y; }
;             }
;             *(u32x4*)(d.O0 + o) = ow;
;           }
;           ss += __shfl_xor(ss, 16); ss += __shfl_xor(ss, 32);
;           if (fq == 0) red[wc * 256 + 128 * ai + 16 * m + rb] = ss;
;           asm volatile("" ::: "memory");
;         }
.LBB0_533:
	s_or_b64 exec, exec, s[44:45]
	v_add_u32_e32 v50, 0x90, v132
	s_waitcnt lgkmcnt(0)
	v_ashrrev_i32_e32 v51, 31, v50
	v_lshlrev_b64 v[50:51], 11, v[50:51]
	v_lshl_add_u64 v[50:51], s[28:29], 0, v[50:51]
	v_lshl_add_u64 v[50:51], v[130:131], 1, v[50:51]
	s_waitcnt vmcnt(5)
	v_mov_b32_e32 v52, v244
	v_mov_b32_e32 v53, v245
	v_mov_b32_e32 v54, v246
	v_mov_b32_e32 v55, v247
	s_nop 0
	v_lshlrev_b32_e32 v56, 16, v52
	v_and_b32_e32 v57, 0xffff0000, v52
	v_lshlrev_b32_e32 v52, 16, v53
	v_and_b32_e32 v53, 0xffff0000, v53
	v_pk_fma_f32 v[48:49], s[66:67], v[48:49], v[52:53]
	v_pk_fma_f32 v[46:47], s[60:61], v[46:47], v[56:57]
	v_mul_f32_e32 v53, v49, v49
	v_mul_f32_e32 v52, v47, v47
	v_fmac_f32_e32 v52, v46, v46
	v_fmac_f32_e32 v53, v48, v48
	v_add_f32_e32 v56, v52, v53
	v_cvt_pk_bf16_f32 v46, v46, v47
	v_cvt_pk_bf16_f32 v47, v48, v49
	v_lshlrev_b32_e32 v48, 16, v54
	v_and_b32_e32 v49, 0xffff0000, v54
	v_lshlrev_b32_e32 v52, 16, v55
	v_and_b32_e32 v53, 0xffff0000, v55
	v_pk_fma_f32 v[44:45], s[66:67], v[44:45], v[52:53]
	v_pk_fma_f32 v[42:43], s[60:61], v[42:43], v[48:49]
	v_mul_f32_e32 v49, v45, v45
	v_mul_f32_e32 v48, v43, v43
	v_fmac_f32_e32 v48, v42, v42
	v_fmac_f32_e32 v49, v44, v44
	v_add_f32_e32 v48, v48, v49
	v_add_f32_e32 v52, v56, v48
	v_cvt_pk_bf16_f32 v48, v42, v43
	v_cvt_pk_bf16_f32 v49, v44, v45
	s_waitcnt vmcnt(4)
	v_mov_b32_e32 v42, v248
	v_mov_b32_e32 v43, v249
	v_mov_b32_e32 v44, v250
	v_mov_b32_e32 v45, v251
	s_nop 0
	global_store_dwordx4 v[50:51], v[46:49], off
	s_nop 0
	s_nop 0
	v_lshlrev_b32_e32 v46, 16, v42
	v_and_b32_e32 v47, 0xffff0000, v42
	v_lshlrev_b32_e32 v42, 16, v43
	v_and_b32_e32 v43, 0xffff0000, v43
	v_pk_fma_f32 v[40:41], s[66:67], v[40:41], v[42:43]
	v_pk_fma_f32 v[38:39], s[60:61], v[38:39], v[46:47]
	v_mul_f32_e32 v43, v41, v41
	v_mul_f32_e32 v42, v39, v39
	v_fmac_f32_e32 v42, v38, v38
	v_fmac_f32_e32 v43, v40, v40
	v_add_f32_e32 v42, v42, v43
	v_add_f32_e32 v46, v52, v42
	v_cvt_pk_bf16_f32 v38, v38, v39
	v_cvt_pk_bf16_f32 v39, v40, v41
	v_lshlrev_b32_e32 v40, 16, v44
	v_and_b32_e32 v41, 0xffff0000, v44
	v_lshlrev_b32_e32 v42, 16, v45
	v_and_b32_e32 v43, 0xffff0000, v45
	v_pk_fma_f32 v[36:37], s[66:67], v[36:37], v[42:43]
	v_pk_fma_f32 v[34:35], s[60:61], v[34:35], v[40:41]
	v_mul_f32_e32 v41, v37, v37
	v_mul_f32_e32 v40, v35, v35
	v_fmac_f32_e32 v40, v34, v34
	v_fmac_f32_e32 v41, v36, v36
	v_add_f32_e32 v40, v40, v41
	v_add_f32_e32 v42, v40, v46
	v_cvt_pk_bf16_f32 v40, v34, v35
	ds_bpermute_b32 v34, v116, v42
	v_cvt_pk_bf16_f32 v41, v36, v37
	global_store_dwordx4 v[50:51], v[38:41], off offset:256
	s_waitcnt lgkmcnt(0)
	v_add_f32_e32 v34, v42, v34
	ds_bpermute_b32 v35, v117, v34
	s_and_saveexec_b64 s[44:45], vcc
	s_cbranch_execz .LBB0_535
	s_waitcnt lgkmcnt(0)
	v_add_f32_e32 v34, v34, v35
	ds_write_b32 v0, v34 offset:576
; DI u32x2 pk4(f32x4 v) { u32x2 r; r.x = cvt_pk(v[0], v[1]); r.y = cvt_pk(v[2], v[3]); return r; }
; DI void gemm_phase(LAS unsigned char* lds, const GemmDesc& d, float* __restrict__ X) {
;     ...
; #pragma unroll
;       for (int ai = 0; ai < 2; ++ai)
; #pragma unroll
;         for (int m = 0; m < 4; ++m) {
;           const int row = pm * 256 + 128 * ai + 16 * m + rb; float ss = 0.f;
; #pragma unroll
;           for (int bj = 0; bj < 2; ++bj) {
;             const size_t o = (size_t)row * DM + pn * 256 + 128 * bj + cb;
;             const u32x4 xw = *(const u32x4*)(d.O0 + o); u32x4 ow;
; #pragma unroll
;             for (int n = 0; n < 2; ++n) {
;               const unsigned w0 = n ? xw.z : xw.x, w1 = n ? xw.w : xw.y;
;               f32x4 xo; xo[0] = __uint_as_float(w0 << 16); xo[1] = __uint_as_float(w0 & 0xffff0000u); xo[2] = __uint_as_float(w1 << 16); xo[3] = __uint_as_float(w1 & 0xffff0000u);
;               const f32x4 xn = xo + acc[ai][bj][m][n] * alpha;
;               ss += (xn[0] * xn[0] + xn[1] * xn[1]) + (xn[2] * xn[2] + xn[3] * xn[3]);
;               const u32x2 pw = pk4(xn); if (n) { ow.z = pw.x; ow.w = pw.y; } else { ow.x = pw.x; ow.y = pw.y; }
;             }
;             *(u32x4*)(d.O0 + o) = ow;
;           }
;           ss += __shfl_xor(ss, 16); ss += __shfl_xor(ss, 32);
;           if (fq == 0) red[wc * 256 + 128 * ai + 16 * m + rb] = ss;
;           asm volatile("" ::: "memory");
;         }
.LBB0_535:
	s_or_b64 exec, exec, s[44:45]
	v_add_u32_e32 v34, 0xa0, v132
	s_waitcnt lgkmcnt(0)
	v_ashrrev_i32_e32 v35, 31, v34
	v_lshlrev_b64 v[34:35], 11, v[34:35]
	v_lshl_add_u64 v[34:35], s[28:29], 0, v[34:35]
	v_lshl_add_u64 v[34:35], v[130:131], 1, v[34:35]
	s_waitcnt vmcnt(3)
	v_mov_b32_e32 v36, v142
	v_mov_b32_e32 v37, v143
	v_mov_b32_e32 v38, v144
	v_mov_b32_e32 v39, v145
	s_nop 0
	v_lshlrev_b32_e32 v40, 16, v36
	v_and_b32_e32 v41, 0xffff0000, v36
	v_lshlrev_b32_e32 v36, 16, v37
	v_and_b32_e32 v37, 0xffff0000, v37
	v_pk_fma_f32 v[32:33], s[66:67], v[32:33], v[36:37]
	v_pk_fma_f32 v[30:31], s[60:61], v[30:31], v[40:41]
	v_mul_f32_e32 v37, v33, v33
	v_mul_f32_e32 v36, v31, v31
	v_fmac_f32_e32 v36, v30, v30
	v_fmac_f32_e32 v37, v32, v32
	v_add_f32_e32 v40, v36, v37
	v_cvt_pk_bf16_f32 v30, v30, v31
	v_cvt_pk_bf16_f32 v31, v32, v33
	v_lshlrev_b32_e32 v32, 16, v38
	v_and_b32_e32 v33, 0xffff0000, v38
	v_lshlrev_b32_e32 v36, 16, v39
	v_and_b32_e32 v37, 0xffff0000, v39
	v_pk_fma_f32 v[28:29], s[66:67], v[28:29], v[36:37]
	v_pk_fma_f32 v[26:27], s[60:61], v[26:27], v[32:33]
	v_mul_f32_e32 v33, v29, v29
	v_mul_f32_e32 v32, v27, v27
	v_fmac_f32_e32 v32, v26, v26
	v_fmac_f32_e32 v33, v28, v28
	v_add_f32_e32 v32, v32, v33
	v_add_f32_e32 v36, v40, v32
	v_cvt_pk_bf16_f32 v32, v26, v27
	v_cvt_pk_bf16_f32 v33, v28, v29
	s_waitcnt vmcnt(2)
	v_mov_b32_e32 v26, v166
	v_mov_b32_e32 v27, v167
	v_mov_b32_e32 v28, v168
	v_mov_b32_e32 v29, v169
	s_nop 0
	global_store_dwordx4 v[34:35], v[30:33], off
	s_nop 0
	s_nop 0
	v_lshlrev_b32_e32 v30, 16, v26
	v_and_b32_e32 v31, 0xffff0000, v26
	v_lshlrev_b32_e32 v26, 16, v27
	v_and_b32_e32 v27, 0xffff0000, v27
	v_pk_fma_f32 v[24:25], s[66:67], v[24:25], v[26:27]
	v_pk_fma_f32 v[22:23], s[60:61], v[22:23], v[30:31]
	v_mul_f32_e32 v27, v25, v25
	v_mul_f32_e32 v26, v23, v23
	v_fmac_f32_e32 v26, v22, v22
	v_fmac_f32_e32 v27, v24, v24
	v_add_f32_e32 v26, v26, v27
	v_add_f32_e32 v30, v36, v26
	v_cvt_pk_bf16_f32 v22, v22, v23
	v_cvt_pk_bf16_f32 v23, v24, v25
	v_lshlrev_b32_e32 v24, 16, v28
	v_and_b32_e32 v25, 0xffff0000, v28
	v_lshlrev_b32_e32 v26, 16, v29
	v_and_b32_e32 v27, 0xffff0000, v29
	v_pk_fma_f32 v[20:21], s[66:67], v[20:21], v[26:27]
	v_pk_fma_f32 v[18:19], s[60:61], v[18:19], v[24:25]
	v_mul_f32_e32 v25, v21, v21
	v_mul_f32_e32 v24, v19, v19
	v_fmac_f32_e32 v24, v18, v18
	v_fmac_f32_e32 v25, v20, v20
	v_add_f32_e32 v24, v24, v25
	v_add_f32_e32 v26, v24, v30
	v_cvt_pk_bf16_f32 v24, v18, v19
	ds_bpermute_b32 v18, v116, v26
	v_cvt_pk_bf16_f32 v25, v20, v21
	global_store_dwordx4 v[34:35], v[22:25], off offset:256
	s_waitcnt lgkmcnt(0)
	v_add_f32_e32 v18, v26, v18
	ds_bpermute_b32 v19, v117, v18
	s_and_saveexec_b64 s[44:45], vcc
	s_cbranch_execz .LBB0_537
	s_waitcnt lgkmcnt(0)
	v_add_f32_e32 v18, v18, v19
	ds_write_b32 v0, v18 offset:640
.LBB0_537:
	s_or_b64 exec, exec, s[44:45]
	v_add_u32_e32 v18, 0xb0, v132
	s_waitcnt lgkmcnt(0)
	v_ashrrev_i32_e32 v19, 31, v18
	v_lshlrev_b64 v[18:19], 11, v[18:19]
	v_lshl_add_u64 v[18:19], s[28:29], 0, v[18:19]
	v_lshl_add_u64 v[18:19], v[130:131], 1, v[18:19]
	s_waitcnt vmcnt(1)
	v_mov_b32_e32 v20, v170
	v_mov_b32_e32 v21, v171
	v_mov_b32_e32 v22, v172
	v_mov_b32_e32 v23, v173
	s_nop 0
	v_lshlrev_b32_e32 v24, 16, v20
	v_and_b32_e32 v25, 0xffff0000, v20
	v_lshlrev_b32_e32 v20, 16, v21
	v_and_b32_e32 v21, 0xffff0000, v21
	v_pk_fma_f32 v[16:17], s[66:67], v[16:17], v[20:21]
	v_pk_fma_f32 v[14:15], s[60:61], v[14:15], v[24:25]
	v_mul_f32_e32 v21, v17, v17
	v_mul_f32_e32 v20, v15, v15
	v_fmac_f32_e32 v20, v14, v14
	v_fmac_f32_e32 v21, v16, v16
	v_add_f32_e32 v24, v20, v21
	v_cvt_pk_bf16_f32 v14, v14, v15
	v_cvt_pk_bf16_f32 v15, v16, v17
	v_lshlrev_b32_e32 v16, 16, v22
	v_and_b32_e32 v17, 0xffff0000, v22
	v_lshlrev_b32_e32 v20, 16, v23
	v_and_b32_e32 v21, 0xffff0000, v23
	v_pk_fma_f32 v[12:13], s[66:67], v[12:13], v[20:21]
	v_pk_fma_f32 v[10:11], s[60:61], v[10:11], v[16:17]
	v_mul_f32_e32 v17, v13, v13
	v_mul_f32_e32 v16, v11, v11
	v_fmac_f32_e32 v16, v10, v10
	v_fmac_f32_e32 v17, v12, v12
	v_add_f32_e32 v16, v16, v17
	v_add_f32_e32 v20, v24, v16
	v_cvt_pk_bf16_f32 v16, v10, v11
	v_cvt_pk_bf16_f32 v17, v12, v13
	s_waitcnt vmcnt(0)
	v_mov_b32_e32 v10, v184
	v_mov_b32_e32 v11, v185
	v_mov_b32_e32 v12, v186
	v_mov_b32_e32 v13, v187
	s_nop 0
	global_store_dwordx4 v[18:19], v[14:17], off
	s_nop 0
	s_nop 0
	v_lshlrev_b32_e32 v14, 16, v10
	v_and_b32_e32 v15, 0xffff0000, v10
	v_lshlrev_b32_e32 v10, 16, v11
	v_and_b32_e32 v11, 0xffff0000, v11
	v_pk_fma_f32 v[8:9], s[66:67], v[8:9], v[10:11]
	v_pk_fma_f32 v[6:7], s[60:61], v[6:7], v[14:15]
	v_mul_f32_e32 v11, v9, v9
	v_mul_f32_e32 v10, v7, v7
	v_fmac_f32_e32 v10, v6, v6
	v_fmac_f32_e32 v11, v8, v8
	v_add_f32_e32 v10, v10, v11
	v_add_f32_e32 v14, v20, v10
	v_cvt_pk_bf16_f32 v6, v6, v7
	v_cvt_pk_bf16_f32 v7, v8, v9
	v_lshlrev_b32_e32 v8, 16, v12
	v_and_b32_e32 v9, 0xffff0000, v12
	v_lshlrev_b32_e32 v10, 16, v13
	v_and_b32_e32 v11, 0xffff0000, v13
	v_pk_fma_f32 v[4:5], s[66:67], v[4:5], v[10:11]
	v_pk_fma_f32 v[2:3], s[60:61], v[2:3], v[8:9]
	v_mul_f32_e32 v9, v5, v5
	v_mul_f32_e32 v8, v3, v3
	v_fmac_f32_e32 v8, v2, v2
	v_fmac_f32_e32 v9, v4, v4
	v_add_f32_e32 v8, v8, v9
	v_add_f32_e32 v10, v8, v14
	v_cvt_pk_bf16_f32 v8, v2, v3
	ds_bpermute_b32 v2, v116, v10
	v_cvt_pk_bf16_f32 v9, v4, v5
	global_store_dwordx4 v[18:19], v[6:9], off offset:256
	s_waitcnt lgkmcnt(0)
	v_add_f32_e32 v2, v10, v2
	ds_bpermute_b32 v3, v117, v2
	s_and_saveexec_b64 s[44:45], vcc
	s_cbranch_execz .LBB0_539
	s_waitcnt lgkmcnt(0)
	v_add_f32_e32 v2, v2, v3
	ds_write_b32 v0, v2 offset:704
